# 32-bit offset addressing for the ssd_sample row loads, the ssd_prompt next-chunk row prefetch (unpredicated, scalar-base stepping) and the in-projection epilogue stores
# speedup vs baseline: 1.0240x; 1.0068x over previous
.LBB0_301:
	v_lshl_or_b32 v150, s60, 8, v154
	v_ashrrev_i32_e32 v151, 31, v150
	s_nop 0
	v_lshlrev_b32_e64 v150, 1, v150
	v_mad_u32_u24 v158, v146, s59, v150
	s_nop 0
	s_nop 0
	v_cvt_pk_bf16_f32 v124, v124, v125
	v_cvt_pk_bf16_f32 v125, v126, v127
	v_cvt_pk_bf16_f32 v126, v120, v121
	v_cvt_pk_bf16_f32 v127, v122, v123
	global_store_dwordx4 v158, v[124:127], s[12:13]
	v_cvt_pk_bf16_f32 v112, v112, v113
	v_cvt_pk_bf16_f32 v113, v114, v115
	v_cvt_pk_bf16_f32 v114, v104, v105
	v_or_b32_e32 v104, 16, v146
	v_mad_u32_u24 v104, v104, s59, v150
	v_cvt_pk_bf16_f32 v115, v106, v107
	global_store_dwordx4 v158, v[112:115], s[12:13] offset:256
	s_nop 1
	v_mov_b32_e64 v112, v104
	v_cvt_pk_bf16_f32 v104, v116, v117
	v_cvt_pk_bf16_f32 v105, v118, v119
	v_cvt_pk_bf16_f32 v106, v108, v109
	v_cvt_pk_bf16_f32 v107, v110, v111
	global_store_dwordx4 v112, v[104:107], s[12:13]
	v_cvt_pk_bf16_f32 v96, v96, v97
	v_cvt_pk_bf16_f32 v97, v98, v99
	v_cvt_pk_bf16_f32 v98, v88, v89
	v_or_b32_e32 v88, 32, v146
	v_mad_u32_u24 v88, v88, s59, v150
	v_cvt_pk_bf16_f32 v99, v90, v91
	global_store_dwordx4 v112, v[96:99], s[12:13] offset:256
	s_nop 1
	v_mov_b32_e64 v96, v88
	v_cvt_pk_bf16_f32 v88, v100, v101
	v_cvt_pk_bf16_f32 v89, v102, v103
	v_cvt_pk_bf16_f32 v90, v92, v93
	v_cvt_pk_bf16_f32 v91, v94, v95
	global_store_dwordx4 v96, v[88:91], s[12:13]
	v_cvt_pk_bf16_f32 v80, v80, v81
	v_cvt_pk_bf16_f32 v81, v82, v83
	v_cvt_pk_bf16_f32 v82, v72, v73
	v_or_b32_e32 v72, 48, v146
	v_mad_u32_u24 v72, v72, s59, v150
	v_cvt_pk_bf16_f32 v83, v74, v75
	global_store_dwordx4 v96, v[80:83], s[12:13] offset:256
	s_nop 1
	v_mov_b32_e64 v80, v72
	v_cvt_pk_bf16_f32 v72, v84, v85
	v_cvt_pk_bf16_f32 v73, v86, v87
	v_cvt_pk_bf16_f32 v74, v76, v77
	v_cvt_pk_bf16_f32 v75, v78, v79
	global_store_dwordx4 v80, v[72:75], s[12:13]
	v_cvt_pk_bf16_f32 v68, v68, v69
	v_cvt_pk_bf16_f32 v69, v70, v71
	v_cvt_pk_bf16_f32 v70, v64, v65
	v_add_u32_e32 v64, 0x80, v146
	v_mad_u32_u24 v64, v64, s59, v150
	s_nop 0
	s_nop 0
	v_cvt_pk_bf16_f32 v71, v66, v67
	global_store_dwordx4 v80, v[68:71], s[12:13] offset:256
	v_cvt_pk_bf16_f32 v60, v60, v61
	v_cvt_pk_bf16_f32 v61, v62, v63
	v_cvt_pk_bf16_f32 v62, v56, v57
	v_cvt_pk_bf16_f32 v63, v58, v59
	global_store_dwordx4 v64, v[60:63], s[12:13]
	v_cvt_pk_bf16_f32 v48, v48, v49
	v_cvt_pk_bf16_f32 v49, v50, v51
	v_cvt_pk_bf16_f32 v50, v40, v41
	v_add_u32_e32 v40, 0x90, v146
	v_mad_u32_u24 v40, v40, s59, v150
	v_cvt_pk_bf16_f32 v51, v42, v43
	global_store_dwordx4 v64, v[48:51], s[12:13] offset:256
	s_nop 1
	v_mov_b32_e64 v48, v40
	v_cvt_pk_bf16_f32 v40, v52, v53
	v_cvt_pk_bf16_f32 v41, v54, v55
	v_cvt_pk_bf16_f32 v42, v44, v45
	v_cvt_pk_bf16_f32 v43, v46, v47
	global_store_dwordx4 v48, v[40:43], s[12:13]
	v_cvt_pk_bf16_f32 v32, v32, v33
	v_cvt_pk_bf16_f32 v33, v34, v35
	v_cvt_pk_bf16_f32 v34, v24, v25
	v_add_u32_e32 v24, 0xa0, v146
	v_mad_u32_u24 v24, v24, s59, v150
	v_cvt_pk_bf16_f32 v35, v26, v27
	global_store_dwordx4 v48, v[32:35], s[12:13] offset:256
	s_nop 1
	v_mov_b32_e64 v32, v24
	v_cvt_pk_bf16_f32 v24, v36, v37
	v_cvt_pk_bf16_f32 v25, v38, v39
	v_cvt_pk_bf16_f32 v26, v28, v29
	v_cvt_pk_bf16_f32 v27, v30, v31
	global_store_dwordx4 v32, v[24:27], s[12:13]
	v_cvt_pk_bf16_f32 v16, v16, v17
	v_cvt_pk_bf16_f32 v17, v18, v19
	v_cvt_pk_bf16_f32 v18, v8, v9
	v_add_u32_e32 v8, 0xb0, v146
	v_mad_u32_u24 v8, v8, s59, v150
	v_cvt_pk_bf16_f32 v19, v10, v11
	global_store_dwordx4 v32, v[16:19], s[12:13] offset:256
	s_nop 1
	v_mov_b32_e64 v16, v8
	v_cvt_pk_bf16_f32 v8, v20, v21
	v_cvt_pk_bf16_f32 v9, v22, v23
	v_cvt_pk_bf16_f32 v10, v12, v13
	v_cvt_pk_bf16_f32 v11, v14, v15
	global_store_dwordx4 v16, v[8:11], s[12:13]
	v_cvt_pk_bf16_f32 v4, v4, v5
	v_cvt_pk_bf16_f32 v5, v6, v7
	v_cvt_pk_bf16_f32 v6, v0, v1
	v_cvt_pk_bf16_f32 v7, v2, v3
	global_store_dwordx4 v16, v[4:7], s[12:13] offset:256
	s_andn2_b64 vcc, exec, s[6:7]
	s_mov_b64 s[6:7], -1
	s_cbranch_vccnz .LBB0_288

.LBB0_922:
	s_and_b64 vcc, exec, s[6:7]
	s_cbranch_vccz .LBB0_1448
	s_load_dwordx4 s[12:15], s[72:73], 0x120
	s_waitcnt vmcnt(5)
	v_mov_b32_e32 v37, v174
	s_add_i32 s3, s2, 0xffffff00
	s_load_dwordx2 s[4:5], s[72:73], 0x70
	s_load_dwordx2 s[10:11], s[72:73], 0x10
	s_and_b32 s7, s2, 15
	s_lshr_b32 s9, s3, 4
	s_waitcnt lgkmcnt(0)
	s_add_u32 s22, s14, 0x2800000
	s_addc_u32 s23, s15, 0
	s_lshl_b32 s6, s7, 2
	v_mov_b32_e32 v0, s6
	global_load_dword v17, v0, s[4:5]
	v_ashrrev_i32_e32 v20, 3, v37
	s_lshl_b32 s5, s9, 10
	s_lshl_b32 s4, s7, 6
	s_mov_b32 s19, 0
	s_or_b32 s18, s5, s4
	v_ashrrev_i32_e32 v21, 31, v20
	v_lshl_add_u64 v[18:19], v[20:21], 0, s[18:19]
	s_lshl_b32 s3, s9, 3
	v_and_b32_e32 v36, 7, v37
	v_lshlrev_b64 v[0:1], 9, v[18:19]
	v_lshl_add_u64 v[0:1], s[10:11], 0, v[0:1]
	v_mov_b32_e32 v3, 0
	v_lshlrev_b32_e32 v2, 6, v36
	s_or_b32 s43, s3, 0x4000
	v_lshl_add_u64 v[22:23], v[0:1], 0, v[2:3]
	s_mul_i32 s30, s43, 0x1700
	s_or_b32 s42, s3, 0x4001
	global_load_dwordx4 v[0:3], v[22:23], off offset:48
	global_load_dwordx4 v[4:7], v[22:23], off offset:32
	global_load_dwordx4 v[8:11], v[22:23], off offset:16
	global_load_dwordx4 v[12:15], v[22:23], off
	v_lshlrev_b32_e64 v22, 1, v20
	s_or_b32 s18, s30, s4
	s_mul_i32 s28, s42, 0x1700
	s_or_b32 s41, s3, 0x4002
	v_lshl_add_u32 v24, s18, 1, v22
	s_add_i32 s18, s28, s4
	s_mul_i32 s26, s41, 0x1700
	s_or_b32 s40, s3, 0x4003
	s_waitcnt vmcnt(9)
	v_lshl_add_u32 v34, s18, 1, v22
	s_add_i32 s18, s26, s4
	s_mul_i32 s24, s40, 0x1700
	s_or_b32 s39, s3, 0x4004
	v_lshl_add_u32 v38, s18, 1, v22
	s_add_i32 s18, s24, s4
	s_mul_i32 s20, s39, 0x1700
	s_or_b32 s38, s3, 0x4005
	v_lshl_add_u32 v40, s18, 1, v22
	s_or_b32 s18, s20, s4
	s_mul_i32 s16, s38, 0x1700
	s_or_b32 s5, s3, 0x4006
	s_waitcnt vmcnt(8)
	v_lshl_add_u32 v42, s18, 1, v22
	s_add_i32 s18, s16, s4
	s_mul_i32 s10, s5, 0x1700
	s_or_b32 s3, s3, 0x4007
	v_lshl_add_u32 v44, s18, 1, v22
	s_add_i32 s18, s10, s4
	s_mul_i32 s8, s3, 0x1700
	s_waitcnt vmcnt(7)
	v_lshl_add_u32 v46, s18, 1, v22
	s_add_i32 s18, s8, s4
	v_lshl_add_u32 v22, s18, 1, v22
	global_load_ushort v16, v24, s[22:23]
	global_load_ushort v31, v34, s[22:23]
	global_load_ushort v29, v38, s[22:23]
	global_load_ushort v28, v40, s[22:23]
	global_load_ushort v27, v42, s[22:23]
	global_load_ushort v26, v44, s[22:23]
	global_load_ushort v30, v46, s[22:23]
	global_load_ushort v32, v22, s[22:23]
	s_movk_i32 s7, 0x13f
	v_cmp_lt_i32_e32 vcc, s7, v37
	s_and_saveexec_b64 s[18:19], vcc
	s_xor_b64 s[18:19], exec, s[18:19]
	s_cbranch_execz .LBB0_931
	s_movk_i32 s7, 0x148
	v_cmp_gt_u32_e32 vcc, s7, v37
	s_and_saveexec_b64 s[34:35], vcc
	s_cbranch_execz .LBB0_930
	v_add_u32_e32 v22, s43, v37
	v_add_u32_e32 v22, 0xfffffec0, v22
	v_mov_b32_e32 v23, 0
	v_lshlrev_b64 v[22:23], 6, v[22:23]
	s_load_dwordx4 s[44:47], s[72:73], 0x60
	s_mov_b32 s7, 0
	v_lshl_add_u64 v[22:23], s[14:15], 0, v[22:23]
	v_lshl_add_u64 v[22:23], v[22:23], 0, s[6:7]
	v_add_co_u32_e32 v22, vcc, 0xec00000, v22
	v_mov_b32_e32 v24, s6
	s_nop 0
	v_addc_co_u32_e32 v23, vcc, 0, v23, vcc
	global_load_dword v22, v[22:23], off
	s_waitcnt lgkmcnt(0)
	global_load_dword v25, v24, s[44:45]
	global_load_dword v23, v24, s[46:47]
	s_mov_b32 s6, 0xbfb8aa3b
	s_waitcnt vmcnt(1)
	v_add_f32_e32 v22, v25, v22
	v_mul_f32_e64 v24, |v22|, s6
	v_exp_f32_e32 v25, v24
	s_mov_b32 s6, 0x3c23d70a
	v_cmp_ngt_f32_e32 vcc, s6, v25
	s_and_saveexec_b64 s[6:7], vcc
	s_xor_b64 s[36:37], exec, s[6:7]
	s_cbranch_execz .LBB0_927
	v_add_f32_e32 v24, 1.0, v25
	s_mov_b32 s6, 0x800000
	v_cmp_gt_f32_e32 vcc, s6, v24
	s_mov_b32 s6, 0x3f317217
	s_nop 0
	v_cndmask_b32_e64 v25, 0, 32, vcc
	v_ldexp_f32 v24, v24, v25
	v_log_f32_e32 v24, v24
	s_nop 0
	v_mul_f32_e32 v25, 0x3f317217, v24
	v_fma_f32 v25, v24, s6, -v25
	v_fmamk_f32 v25, v24, 0x3377d1cf, v25
	s_mov_b32 s6, 0x7f800000
	v_fmac_f32_e32 v25, 0x3f317217, v24
	v_cmp_lt_f32_e64 s[6:7], |v24|, s6
	s_nop 1
	v_cndmask_b32_e64 v24, v24, v25, s[6:7]
	v_mov_b32_e32 v25, 0x41b17218
	v_cndmask_b32_e32 v25, 0, v25, vcc
	v_sub_f32_e32 v24, v24, v25

.LBB0_938:
	s_or_saveexec_b64 s[6:7], s[6:7]
	v_mov_b32_e32 v35, 0x80
	s_xor_b64 exec, exec, s[6:7]
	v_add_u32_e32 v24, s4, v37
	v_add_u32_e32 v22, 0x400, v24
	v_lshl_add_u32 v34, v37, 2, 0
	v_mov_b32_e32 v35, 64
	s_or_b64 exec, exec, s[6:7]
	s_load_dwordx4 s[44:47], s[72:73], 0x50
	s_load_dwordx2 s[6:7], s[72:73], 0x18
	v_ashrrev_i32_e32 v25, 31, v24
	v_lshlrev_b64 v[24:25], 2, v[24:25]
	s_mov_b32 s35, 0
	s_waitcnt lgkmcnt(0)
	v_lshl_add_u64 v[38:39], s[44:45], 0, v[24:25]
	v_add_co_u32_e32 v40, vcc, 0x1000, v38
	s_mul_i32 s34, s9, 0x1200
	s_nop 0
	v_addc_co_u32_e32 v41, vcc, 0, v39, vcc
	s_lshl_b64 s[44:45], s[34:35], 2
	v_add_co_u32_e32 v42, vcc, 0x3000, v38
	s_add_u32 s6, s6, s44
	s_nop 0
	v_addc_co_u32_e32 v43, vcc, 0, v39, vcc
	s_addc_u32 s7, s7, s45
	s_movk_i32 s11, 0x1000
	global_load_dword v50, v[38:39], off
	global_load_dword v51, v[40:41], off offset:2048
	global_load_dword v52, v[42:43], off
	v_add_co_u32_e32 v38, vcc, 0x4000, v38
	v_lshl_add_u64 v[40:41], s[46:47], 0, v[24:25]
	v_lshl_add_u64 v[24:25], s[6:7], 0, v[24:25]
	v_ashrrev_i32_e32 v23, 31, v22
	global_load_dword v53, v[40:41], off
	s_mov_b64 s[6:7], vcc
	v_add_co_u32_e32 v40, vcc, s11, v24
	v_lshlrev_b32_e64 v22, 1, v22
	s_mov_b32 s31, s35
	s_movk_i32 s17, 0x3000
	v_addc_co_u32_e32 v41, vcc, 0, v25, vcc
	v_lshl_add_u32 v42, s30, 1, v22
	s_mov_b32 s29, s35
	s_mov_b32 s27, s35
	s_mov_b32 s25, s35
	v_lshl_add_u32 v44, s28, 1, v22
	v_lshl_add_u32 v46, s26, 1, v22
	v_lshl_add_u32 v48, s24, 1, v22
	global_load_ushort v42, v42, s[22:23]
	s_nop 0
	global_load_ushort v43, v44, s[22:23]
	global_load_ushort v54, v46, s[22:23]
	global_load_ushort v55, v48, s[22:23]
	global_load_dword v56, v[24:25], off
	global_load_dword v57, v[40:41], off offset:2048
	v_add_co_u32_e32 v24, vcc, s17, v24
	s_mov_b32 s21, s35
	s_nop 0
	v_addc_co_u32_e32 v25, vcc, 0, v25, vcc
	global_load_dword v40, v[24:25], off
	v_addc_co_u32_e64 v39, vcc, 0, v39, s[6:7]
	global_load_dword v38, v[38:39], off offset:2048
	v_lshl_add_u32 v24, s20, 1, v22
	global_load_ushort v39, v24, s[22:23]
	s_mov_b32 s17, s35
	v_lshl_add_u32 v24, s16, 1, v22
	s_mov_b32 s11, s35
	global_load_ushort v41, v24, s[22:23]
	v_lshl_add_u32 v24, s10, 1, v22
	s_mov_b32 s9, s35
	global_load_ushort v24, v24, s[22:23]
	v_lshl_add_u32 v22, s8, 1, v22
	global_load_ushort v22, v22, s[22:23]
	v_lshl_add_u32 v23, v35, 2, v34
	s_waitcnt vmcnt(11)
	v_lshlrev_b32_e32 v25, 16, v42
	s_waitcnt vmcnt(10)
	v_lshlrev_b32_e32 v42, 16, v43
	v_fma_f32 v45, v50, v25, v53
	s_waitcnt vmcnt(9)
	v_lshlrev_b32_e32 v43, 16, v54
	s_waitcnt vmcnt(7)
	v_fma_f32 v46, v50, v56, v53
	s_waitcnt vmcnt(6)
	v_fmac_f32_e32 v46, v51, v57
	v_fma_f32 v47, v50, v57, v53
	v_fmac_f32_e32 v45, v51, v42
	v_lshlrev_b32_e32 v44, 16, v55
	v_fmac_f32_e32 v45, v52, v43
	s_waitcnt vmcnt(5)
	v_fmac_f32_e32 v46, v52, v40
	v_fmac_f32_e32 v47, v51, v40
	v_fma_f32 v40, v50, v40, v53
	s_waitcnt vmcnt(4)
	v_fmac_f32_e32 v46, v38, v25
	v_fmac_f32_e32 v47, v52, v25
	v_fmac_f32_e32 v40, v51, v25
	v_mul_f32_e32 v25, 0xbfb8aa3b, v46
	v_fmac_f32_e32 v47, v38, v42
	v_exp_f32_e32 v25, v25
	v_mul_f32_e32 v48, 0xbfb8aa3b, v47
	v_exp_f32_e32 v48, v48
	v_fmac_f32_e32 v40, v52, v42
	v_fmac_f32_e32 v40, v38, v43
	v_add_f32_e32 v25, 1.0, v25
	v_mul_f32_e32 v49, 0xbfb8aa3b, v40
	v_rcp_f32_e32 v25, v25
	v_add_f32_e32 v48, 1.0, v48
	v_rcp_f32_e32 v48, v48
	v_exp_f32_e32 v49, v49
	v_mul_f32_e32 v25, v46, v25
	ds_write_b32 v34, v25
	v_mul_f32_e32 v25, v47, v48
	v_add_f32_e32 v47, 1.0, v49
	v_rcp_f32_e32 v47, v47
	ds_write_b32 v23, v25
	v_fmac_f32_e32 v45, v38, v44
	s_waitcnt vmcnt(3)
	v_lshlrev_b32_e32 v39, 16, v39
	v_mul_f32_e32 v25, v40, v47
	v_lshl_add_u32 v40, v35, 3, v34
	ds_write_b32 v40, v25
	v_fma_f32 v40, v50, v42, v53
	v_fmac_f32_e32 v40, v51, v43
	v_fmac_f32_e32 v40, v52, v44
	v_mul_f32_e32 v46, 0xbfb8aa3b, v45
	v_fmac_f32_e32 v40, v38, v39
	v_exp_f32_e32 v46, v46
	v_mul_f32_e32 v42, 0xbfb8aa3b, v40
	v_exp_f32_e32 v42, v42
	v_mad_u32_u24 v25, v35, 12, v34
	v_add_f32_e32 v23, 1.0, v46
	v_rcp_f32_e32 v23, v23
	v_add_f32_e32 v42, 1.0, v42
	v_rcp_f32_e32 v42, v42
	v_fma_f32 v43, v50, v43, v53
	v_mul_f32_e32 v23, v45, v23
	ds_write_b32 v25, v23
	v_mul_f32_e32 v25, v40, v42
	v_lshl_add_u32 v40, v35, 4, v34
	v_fmac_f32_e32 v43, v51, v44
	ds_write_b32 v40, v25
	v_fma_f32 v40, v50, v44, v53
	s_waitcnt vmcnt(2)
	v_lshlrev_b32_e32 v41, 16, v41
	v_fmac_f32_e32 v43, v52, v39
	v_fmac_f32_e32 v40, v51, v39
	v_fmac_f32_e32 v53, v50, v39
	v_fmac_f32_e32 v43, v38, v41
	s_waitcnt vmcnt(1)
	v_lshlrev_b32_e32 v24, 16, v24
	v_fmac_f32_e32 v40, v52, v41
	v_fmac_f32_e32 v53, v51, v41
	v_mul_f32_e32 v45, 0xbfb8aa3b, v43
	v_fmac_f32_e32 v40, v38, v24
	s_waitcnt vmcnt(0)
	v_lshlrev_b32_e32 v22, 16, v22
	v_fmac_f32_e32 v53, v52, v24
	v_exp_f32_e32 v45, v45
	v_mul_f32_e32 v42, 0xbfb8aa3b, v40
	v_fmac_f32_e32 v53, v38, v22
	v_exp_f32_e32 v42, v42
	v_mul_f32_e32 v22, 0xbfb8aa3b, v53
	v_exp_f32_e32 v22, v22
	v_add_f32_e32 v23, 1.0, v45
	v_rcp_f32_e32 v23, v23
	v_add_f32_e32 v24, 1.0, v42
	v_rcp_f32_e32 v24, v24
	v_add_f32_e32 v22, 1.0, v22
	v_rcp_f32_e32 v22, v22
	v_mul_f32_e32 v23, v43, v23
	v_mad_u32_u24 v25, v35, 20, v34
	ds_write_b32 v25, v23
	v_mul_f32_e32 v23, v40, v24
	v_mad_u32_u24 v24, v35, 24, v34
	ds_write_b32 v24, v23
	v_mul_f32_e32 v22, v53, v22
	v_mad_u32_u24 v23, v35, 28, v34
	ds_write_b32 v23, v22

.LBB0_1012:
	s_or_b64 exec, exec, s[14:15]
	s_add_i32 s4, s2, 0xffffff80
	s_xor_b64 s[60:61], s[12:13], -1
	s_lshr_b32 s4, s4, 4
	s_add_u32 s12, s54, 0x2800000
	s_addc_u32 s13, s55, 0
	v_mov_b32_e32 v71, 0
	s_lshl_b32 s50, s4, 11
	v_lshlrev_b32_e32 v101, 4, v23
	v_lshl_add_u64 v[72:73], v[70:71], 1, s[12:13]
	s_add_u32 s86, s66, 0x2800000
	s_addc_u32 s87, s67, 0
	v_subrev_u32_e32 v212, s86, v72
	s_and_saveexec_b64 s[14:15], s[10:11]
	s_cbranch_execz .LBB0_1052
	s_movk_i32 s10, 0x4f
	v_cmp_lt_i32_e32 vcc, s10, v22
	v_mov_b32_e32 v70, v71
	s_and_saveexec_b64 s[10:11], vcc
	s_cbranch_execz .LBB0_1015
	v_add3_u32 v20, s50, -3, v101
	s_movk_i32 s16, 0x2e00
	v_mad_u64_u32 v[20:21], s[16:17], v20, s16, v[72:73]
	global_load_dwordx2 v[70:71], v[20:21], off

.LBB0_1129:
	v_add3_u32 v21, v179, s85, 61
	v_mad_u32_u24 v213, v21, s81, v212
	s_mov_b64 s[88:89], s[86:87]
	global_load_dwordx2 v[70:71], v213, s[88:89]
	s_add_u32 s88, s88, 0x2e00
	s_addc_u32 s89, s89, 0
	global_load_dwordx2 v[74:75], v213, s[88:89]
	s_add_u32 s88, s88, 0x2e00
	s_addc_u32 s89, s89, 0
	global_load_dwordx2 v[76:77], v213, s[88:89]
	s_add_u32 s88, s88, 0x2e00
	s_addc_u32 s89, s89, 0
	global_load_dwordx2 v[78:79], v213, s[88:89]
	s_add_u32 s88, s88, 0x2e00
	s_addc_u32 s89, s89, 0
	global_load_dwordx2 v[80:81], v213, s[88:89]
	s_add_u32 s88, s88, 0x2e00
	s_addc_u32 s89, s89, 0
	global_load_dwordx2 v[82:83], v213, s[88:89]
	s_add_u32 s88, s88, 0x2e00
	s_addc_u32 s89, s89, 0
	global_load_dwordx2 v[84:85], v213, s[88:89]
	s_add_u32 s88, s88, 0x2e00
	s_addc_u32 s89, s89, 0
	global_load_dwordx2 v[86:87], v213, s[88:89]
	s_add_u32 s88, s88, 0x2e00
	s_addc_u32 s89, s89, 0
	global_load_dwordx2 v[88:89], v213, s[88:89]
	s_add_u32 s88, s88, 0x2e00
	s_addc_u32 s89, s89, 0
	global_load_dwordx2 v[90:91], v213, s[88:89]
	s_add_u32 s88, s88, 0x2e00
	s_addc_u32 s89, s89, 0
	global_load_dwordx2 v[92:93], v213, s[88:89]
	s_add_u32 s88, s88, 0x2e00
	s_addc_u32 s89, s89, 0
	global_load_dwordx2 v[94:95], v213, s[88:89]
	s_add_u32 s88, s88, 0x2e00
	s_addc_u32 s89, s89, 0
	global_load_dwordx2 v[98:99], v213, s[88:89]
	s_add_u32 s88, s88, 0x2e00
	s_addc_u32 s89, s89, 0
	global_load_dwordx2 v[102:103], v213, s[88:89]
	s_add_u32 s88, s88, 0x2e00
	s_addc_u32 s89, s89, 0
	global_load_dwordx2 v[104:105], v213, s[88:89]
	s_add_u32 s88, s88, 0x2e00
	s_addc_u32 s89, s89, 0
	global_load_dwordx2 v[120:121], v213, s[88:89]
	s_add_u32 s88, s88, 0x2e00
	s_addc_u32 s89, s89, 0
	global_load_dwordx2 v[136:137], v213, s[88:89]
	s_add_u32 s88, s88, 0x2e00
	s_addc_u32 s89, s89, 0
	global_load_dwordx2 v[142:143], v213, s[88:89]
	s_add_u32 s88, s88, 0x2e00
	s_addc_u32 s89, s89, 0
	global_load_dwordx2 v[144:145], v213, s[88:89]
